# stack v71 + lru_item: the never-taken tiny-argument rescale around the 16 sqrtf expansions removed (argument is 0 or >= 2^-24; bit-identical), 80 VALU per item-wave
# speedup vs baseline: 1.0055x; 1.0055x over previous
; #define LAS __attribute__((address_space(3)))
; __device__ __forceinline__ bf16_t f2bf(float f) { return (bf16_t)(pk2(f, 0.f) & 0xffffu); }
; __device__ __forceinline__ float bf2f(unsigned b) { return __uint_as_float(b << 16); }
; __device__ __forceinline__ f32x4 mfma16(bf16x8 a, bf16x8 b, f32x4 c) { return __builtin_amdgcn_mfma_f32_16x16x32_bf16(a, b, c, 0, 0, 0); }
; __device__ __forceinline__ void lds_barrier() { asm volatile("s_waitcnt lgkmcnt(0)" ::: "memory"); __builtin_amdgcn_s_barrier(); asm volatile("" ::: "memory"); }
; __device__ __forceinline__ void lru_item(const Params& p, int l, int item, LAS unsigned char* lds) {
;     ...
; #pragma unroll
;     for (int i = 0; i < 19; ++i) { const int t = t0 - 3 + i; xr[i] = (t >= 0) ? (unsigned)p.z[(Tb + (t >= 0 ? t : 0)) * ZLD + 2304 + ch] : 0u; }
;     bf16x8 wa0[4], wa1[4], wx0[4], wx1[4];
;     { const bf16_t* wap = p.waT + (((size_t)l * 4 + h) * 64 + fr) * 64 + fq * 8; const bf16_t* wxp = p.wxT + (((size_t)l * 4 + h) * 64 + fr) * 64 + fq * 8;
; #pragma unroll
;       for (int jt = 0; jt < 4; ++jt) { wa0[jt] = *(const bf16x8*)(wap + jt * 1024); wa1[jt] = *(const bf16x8*)(wap + jt * 1024 + 32); wx0[jt] = *(const bf16x8*)(wxp + jt * 1024); wx1[jt] = *(const bf16x8*)(wxp + jt * 1024 + 32); } }
;     { const float cb = p.conv_b[l * 256 + ch], cw0 = p.conv_w[(l * 4 + 0) * 256 + ch], cw1 = p.conv_w[(l * 4 + 1) * 256 + ch], cw2 = p.conv_w[(l * 4 + 2) * 256 + ch], cw3 = p.conv_w[(l * 4 + 3) * 256 + ch];
; #pragma unroll
;       for (int i = 0; i < 16; ++i) { const float xc = cb + bf2f(xr[i]) * cw0 + bf2f(xr[i + 1]) * cw1 + bf2f(xr[i + 2]) * cw2 + bf2f(xr[i + 3]) * cw3; xa[i * 72 + lane] = f2bf(xc); xf[i * 66 + lane] = xc; } }
;     lds_barrier();
;     { const bf16x8 a0 = *(const LAS bf16x8*)(xa + fr * 72 + fq * 8), a1 = *(const LAS bf16x8*)(xa + fr * 72 + 32 + fq * 8);
; #pragma unroll
;       for (int jt = 0; jt < 4; ++jt) {
;           f32x4 pa = mfma16(a0, wa0[jt], ZERO4); pa = mfma16(a1, wa1[jt], pa);
;           f32x4 px = mfma16(a0, wx0[jt], ZERO4); px = mfma16(a1, wx1[jt], px);
;           const int cj = l * 256 + h * 64 + jt * 16 + fr; const float bav = p.ba[cj], bxv = p.bx[cj], sp = p.spl[cj];
.LBB0_393:
	s_or_b64 exec, exec, s[74:75]
	s_movk_i32 s4, 0x2a00
	v_and_b32_e32 v91, 15, v1
	s_or_b32 s98, s16, s40
	v_or_b32_e32 v148, s98, v91
	v_ashrrev_i32_e32 v149, 31, v148
	v_lshlrev_b64 v[148:149], 2, v[148:149]
	v_lshl_add_u64 v[150:151], s[30:31], 0, v[148:149]
	v_lshl_add_u64 v[152:153], s[6:7], 0, v[148:149]
	v_lshl_add_u64 v[154:155], s[34:35], 0, v[148:149]
	global_load_dword v156, v[150:151], off
	global_load_dword v157, v[152:153], off
	global_load_dword v158, v[154:155], off
	global_load_dword v159, v[150:151], off offset:64
	global_load_dword v160, v[152:153], off offset:64
	global_load_dword v161, v[154:155], off offset:64
	global_load_dword v162, v[150:151], off offset:128
	global_load_dword v163, v[152:153], off offset:128
	global_load_dword v164, v[154:155], off offset:128
	global_load_dword v165, v[150:151], off offset:192
	global_load_dword v166, v[152:153], off offset:192
	global_load_dword v167, v[154:155], off offset:192
	v_mul_lo_u32 v4, v0, s4
	s_or_b32 s4, s12, s16
	v_add_u32_e32 v79, 0, v4
	v_or_b32_e32 v4, s4, v91
	v_mov_b32_e32 v5, s13
	v_lshlrev_b64 v[4:5], 7, v[4:5]
	v_lshl_add_u64 v[6:7], s[70:71], 0, v[4:5]
	v_and_b32_e32 v20, 48, v3
	v_mov_b32_e32 v21, v2
	v_lshl_add_u64 v[6:7], v[6:7], 0, v[20:21]
	v_lshl_add_u64 v[4:5], s[36:37], 0, v[4:5]
	v_add_co_u32_e32 v8, vcc, s80, v6
	v_lshl_add_u64 v[4:5], v[4:5], 0, v[20:21]
	s_nop 0
	v_addc_co_u32_e32 v9, vcc, 0, v7, vcc
	v_or_b32_e32 v100, s40, v78
	v_mov_b32_e32 v98, s17
	v_mov_b32_e32 v99, s22
	v_add_co_u32_e32 v16, vcc, s80, v4
	v_ashrrev_i32_e32 v101, 31, v100
	s_nop 0
	v_addc_co_u32_e32 v17, vcc, 0, v5, vcc
	v_lshl_add_u64 v[98:99], v[100:101], 2, v[98:99]
	global_load_dwordx4 v[60:63], v[6:7], off
	global_load_dwordx4 v[64:67], v[6:7], off offset:64
	global_load_dwordx4 v[68:71], v[4:5], off
	global_load_dwordx4 v[72:75], v[4:5], off offset:64
	global_load_dwordx4 v[44:47], v[6:7], off offset:2048
	global_load_dwordx4 v[48:51], v[6:7], off offset:2112
	global_load_dwordx4 v[52:55], v[4:5], off offset:2048
	global_load_dwordx4 v[56:59], v[4:5], off offset:2112
	global_load_dwordx4 v[28:31], v[8:9], off
	global_load_dwordx4 v[32:35], v[8:9], off offset:64
	global_load_dwordx4 v[36:39], v[16:17], off
	global_load_dwordx4 v[40:43], v[16:17], off offset:64
	s_nop 0
	global_load_dwordx4 v[4:7], v[8:9], off offset:2048
	s_nop 0
	global_load_dwordx4 v[8:11], v[8:9], off offset:2112
	s_nop 0
	global_load_dwordx4 v[12:15], v[16:17], off offset:2048
	s_nop 0
	global_load_dwordx4 v[16:19], v[16:17], off offset:2112
	v_mov_b32_e32 v96, s33
	global_load_dword v21, v[98:99], off
	v_or_b32_e32 v98, s87, v78
	v_mov_b32_e32 v97, s44
	v_ashrrev_i32_e32 v99, 31, v98
	v_lshl_add_u64 v[96:97], v[98:99], 2, v[96:97]
	global_load_dword v98, v[96:97], off
	global_load_dword v99, v[96:97], off offset:1024
	global_load_dword v100, v[96:97], off offset:2048
	s_nop 0
	global_load_dword v96, v[96:97], off offset:3072
	v_lshlrev_b32_e32 v78, 1, v3
	v_add_u32_e32 v97, v79, v78
	v_add_u32_e32 v80, v97, v78
	s_or_b32 s4, s16, s40
	s_mov_b32 s16, 0xf800000
	v_lshrrev_b32_e32 v92, 4, v3
	v_lshl_add_u32 v1, v1, 3, 0
	v_add_u32_e32 v1, 0x15000, v1
	s_waitcnt vmcnt(3)
	v_lshlrev_b32_e32 v88, 16, v88
	v_lshlrev_b32_e32 v87, 16, v87
	v_lshlrev_b32_e32 v85, 16, v85
	v_lshlrev_b32_e32 v83, 16, v83
	v_lshlrev_b32_e32 v26, 16, v26
	v_lshlrev_b32_e32 v22, 16, v22
	v_lshlrev_b32_e32 v24, 16, v24
	v_lshlrev_b32_e32 v23, 16, v23
	v_lshlrev_b32_e32 v27, 16, v27
	v_lshlrev_b32_e32 v25, 16, v25
	v_lshlrev_b32_e32 v82, 16, v82
	v_lshlrev_b32_e32 v81, 16, v81
	v_lshlrev_b32_e32 v86, 16, v86
	v_lshlrev_b32_e32 v84, 16, v84
	v_lshlrev_b32_e32 v90, 16, v90
	v_lshlrev_b32_e32 v89, 16, v89
	v_lshlrev_b32_e32 v94, 16, v94
	v_lshlrev_b32_e32 v93, 16, v93
	v_lshlrev_b32_e32 v95, 16, v95
	v_cmp_lt_i32_e32 vcc, 2, v76
	s_nop 1
	v_cndmask_b32_e32 v88, 0, v88, vcc
	v_cmp_lt_i32_e32 vcc, 1, v76
	s_nop 1
	v_cndmask_b32_e32 v87, 0, v87, vcc
	v_cmp_lt_i32_e32 vcc, 0, v76
	s_nop 1
	v_cndmask_b32_e32 v85, 0, v85, vcc
	v_fma_f32 v88, v88, v98, v21
	s_waitcnt vmcnt(2)
	v_fmac_f32_e32 v88, v87, v99
	v_fma_f32 v87, v87, v98, v21
	s_waitcnt vmcnt(1)
	v_fmac_f32_e32 v88, v85, v100
	v_fmac_f32_e32 v87, v85, v99
	s_waitcnt vmcnt(0)
	v_fmac_f32_e32 v88, v83, v96
	v_cvt_pk_bf16_f32 v101, v88, v2
	v_fmac_f32_e32 v87, v83, v100
	v_fma_f32 v85, v85, v98, v21
	ds_write_b16 v97, v101
	v_fmac_f32_e32 v87, v26, v96
	v_cvt_pk_bf16_f32 v101, v87, v2
	v_fmac_f32_e32 v85, v83, v99
	v_fma_f32 v83, v83, v98, v21
	ds_write_b16 v97, v101 offset:144
	v_add_u32_e32 v101, 0x800, v80
	v_fmac_f32_e32 v85, v26, v100
	v_fmac_f32_e32 v83, v26, v99
	ds_write2_b32 v101, v88, v87 offset0:64 offset1:130
	v_fmac_f32_e32 v85, v22, v96
	v_cvt_pk_bf16_f32 v87, v85, v2
	v_fmac_f32_e32 v83, v22, v100
	v_fma_f32 v26, v26, v98, v21
	ds_write_b16 v97, v87 offset:288
	v_fmac_f32_e32 v83, v24, v96
	v_cvt_pk_bf16_f32 v87, v83, v2
	v_fmac_f32_e32 v26, v22, v99
	v_fma_f32 v22, v22, v98, v21
	ds_write_b16 v97, v87 offset:432
	v_add_u32_e32 v87, 0xa00, v80
	v_fmac_f32_e32 v26, v24, v100
	v_fmac_f32_e32 v22, v24, v99
	ds_write2_b32 v87, v85, v83 offset0:68 offset1:134
	v_fmac_f32_e32 v26, v23, v96
	v_cvt_pk_bf16_f32 v83, v26, v2
	v_fmac_f32_e32 v22, v23, v100
	ds_write_b16 v97, v83 offset:576
	v_fmac_f32_e32 v22, v27, v96
	v_cvt_pk_bf16_f32 v83, v22, v2
	ds_write_b16 v97, v83 offset:720
	v_add_u32_e32 v83, 0xc00, v80
	ds_write2_b32 v83, v26, v22 offset0:72 offset1:138
	v_fma_f32 v22, v24, v98, v21
	v_fmac_f32_e32 v22, v23, v99
	v_fma_f32 v23, v23, v98, v21
	v_fmac_f32_e32 v22, v27, v100
	v_fmac_f32_e32 v23, v27, v99
	v_fmac_f32_e32 v22, v25, v96
	v_cvt_pk_bf16_f32 v24, v22, v2
; #define LAS __attribute__((address_space(3)))
; __device__ __forceinline__ float fexp(float x) { return __builtin_amdgcn_exp2f(x * LOG2E); }
; __device__ __forceinline__ float sigm(float x) { return frcp(1.f + fexp(-x)); }
; __device__ __forceinline__ f32x4 mfma16(bf16x8 a, bf16x8 b, f32x4 c) { return __builtin_amdgcn_mfma_f32_16x16x32_bf16(a, b, c, 0, 0, 0); }
; __device__ __forceinline__ void lds_barrier() { asm volatile("s_waitcnt lgkmcnt(0)" ::: "memory"); __builtin_amdgcn_s_barrier(); asm volatile("" ::: "memory"); }
; __device__ __forceinline__ void lru_item(const Params& p, int l, int item, LAS unsigned char* lds) {
;     ...
;     lds_barrier();
;     { const bf16x8 a0 = *(const LAS bf16x8*)(xa + fr * 72 + fq * 8), a1 = *(const LAS bf16x8*)(xa + fr * 72 + 32 + fq * 8);
; #pragma unroll
;       for (int jt = 0; jt < 4; ++jt) {
;           f32x4 pa = mfma16(a0, wa0[jt], ZERO4); pa = mfma16(a1, wa1[jt], pa);
;           f32x4 px = mfma16(a0, wx0[jt], ZERO4); px = mfma16(a1, wx1[jt], px);
;           const int cj = l * 256 + h * 64 + jt * 16 + fr; const float bav = p.ba[cj], bxv = p.bx[cj], sp = p.spl[cj];
; #pragma unroll
;           for (int jj = 0; jj < 4; ++jj) { const int t = fq * 4 + jj; const float r = sigm(pa[jj] + bav), ig = sigm(px[jj] + bxv); const float la = -8.f * r * sp;
;               const float a = fexp(la); float mult = sqrtf(fmaxf(1.f - fexp(2.f * la), 0.f)); if (t0 + t == 0) mult = 1.f;
;               const int li = t * 66 + jt * 16 + fr; const float xcv = xf[li]; sa[li] = a; xf[li] = mult * ig * xcv; }
	v_fmac_f32_e32 v23, v25, v100
	ds_write_b16 v97, v24 offset:864
	v_fmac_f32_e32 v23, v82, v96
	v_cvt_pk_bf16_f32 v24, v23, v2
	ds_write_b16 v97, v24 offset:1008
	v_add_u32_e32 v24, 0xe00, v80
	ds_write2_b32 v24, v22, v23 offset0:76 offset1:142
	v_fma_f32 v22, v27, v98, v21
	v_fmac_f32_e32 v22, v25, v99
	v_fmac_f32_e32 v22, v82, v100
	v_fmac_f32_e32 v22, v81, v96
	v_cvt_pk_bf16_f32 v23, v22, v2
	ds_write_b16 v97, v23 offset:1152
	v_fma_f32 v23, v25, v98, v21
	v_fmac_f32_e32 v23, v82, v99
	v_fmac_f32_e32 v23, v81, v100
	v_fmac_f32_e32 v23, v86, v96
	v_cvt_pk_bf16_f32 v24, v23, v2
	ds_write_b16 v97, v24 offset:1296
	v_add_u32_e32 v24, 0x1000, v80
	ds_write2_b32 v24, v22, v23 offset0:80 offset1:146
	v_fma_f32 v22, v82, v98, v21
	v_fmac_f32_e32 v22, v81, v99
	v_fmac_f32_e32 v22, v86, v100
	v_fmac_f32_e32 v22, v84, v96
	v_cvt_pk_bf16_f32 v23, v22, v2
	ds_write_b16 v97, v23 offset:1440
	v_fma_f32 v23, v81, v98, v21
	v_fmac_f32_e32 v23, v86, v99
	v_fmac_f32_e32 v23, v84, v100
	v_fmac_f32_e32 v23, v90, v96
	v_cvt_pk_bf16_f32 v24, v23, v2
	ds_write_b16 v97, v24 offset:1584
	v_add_u32_e32 v24, 0x1200, v80
	ds_write2_b32 v24, v22, v23 offset0:84 offset1:150
	v_fma_f32 v22, v86, v98, v21
	v_fmac_f32_e32 v22, v84, v99
	v_fmac_f32_e32 v22, v90, v100
	v_fmac_f32_e32 v22, v89, v96
	v_cvt_pk_bf16_f32 v23, v22, v2
	ds_write_b16 v97, v23 offset:1728
	v_fma_f32 v23, v84, v98, v21
	v_fmac_f32_e32 v23, v90, v99
	v_fmac_f32_e32 v23, v89, v100
	v_fmac_f32_e32 v23, v94, v96
	v_cvt_pk_bf16_f32 v24, v23, v2
	ds_write_b16 v97, v24 offset:1872
	v_add_u32_e32 v24, 0x1400, v80
	ds_write2_b32 v24, v22, v23 offset0:88 offset1:154
	v_fma_f32 v22, v90, v98, v21
	v_fmac_f32_e32 v22, v89, v99
	v_fmac_f32_e32 v21, v89, v98
	v_fmac_f32_e32 v22, v94, v100
	v_fmac_f32_e32 v21, v94, v99
	v_fmac_f32_e32 v22, v93, v96
	v_cvt_pk_bf16_f32 v23, v22, v2
	v_fmac_f32_e32 v21, v93, v100
	ds_write_b16 v97, v23 offset:2016
	v_fmac_f32_e32 v21, v95, v96
	v_cvt_pk_bf16_f32 v23, v21, v2
	ds_write_b16 v97, v23 offset:2160
	v_add_u32_e32 v23, 0x1600, v80
	ds_write2_b32 v23, v22, v21 offset0:92 offset1:158
	v_mul_u32_u24_e32 v21, 0x90, v91
	s_waitcnt lgkmcnt(0)
	s_barrier
	v_add3_u32 v24, v79, v21, v20
	ds_read_b128 v[20:23], v24
	ds_read_b128 v[24:27], v24 offset:64
	s_waitcnt lgkmcnt(1)
	v_mfma_f32_16x16x32_bf16 v[60:63], v[20:23], v[60:63], 0
	v_or_b32_e32 v86, s4, v91
	v_ashrrev_i32_e32 v87, 31, v86
	s_waitcnt lgkmcnt(0)
	v_mfma_f32_16x16x32_bf16 v[82:85], v[24:27], v[64:67], v[60:63]
	v_mfma_f32_16x16x32_bf16 v[60:63], v[20:23], v[68:71], 0
	v_mfma_f32_16x16x32_bf16 v[70:73], v[24:27], v[72:75], v[60:63]
	v_mfma_f32_16x16x32_bf16 v[44:47], v[20:23], v[44:47], 0
	s_nop 5
	v_lshlrev_b64 v[60:61], 2, v[86:87]
	v_lshl_add_u64 v[64:65], s[30:31], 0, v[60:61]
	v_lshl_add_u64 v[62:63], s[6:7], 0, v[60:61]
	v_lshl_add_u64 v[60:61], s[34:35], 0, v[60:61]
	v_mfma_f32_16x16x32_bf16 v[48:51], v[24:27], v[48:51], v[44:47]
	s_waitcnt vmcnt(0)
	v_mov_b32_e32 v81, v156
	v_mov_b32_e32 v86, v157
	v_mov_b32_e32 v87, v158
	v_add_f32_e32 v66, v82, v81
	v_mul_f32_e32 v66, 0xbfb8aa3b, v66
	v_exp_f32_e32 v66, v66
	s_waitcnt vmcnt(1)
	v_add_f32_e32 v67, v70, v86
	v_mul_f32_e32 v67, 0xbfb8aa3b, v67
	v_exp_f32_e32 v67, v67
	v_add_f32_e32 v66, 1.0, v66
	v_rcp_f32_e32 v66, v66
	v_mfma_f32_16x16x32_bf16 v[44:47], v[20:23], v[52:55], 0
	v_add_f32_e32 v67, 1.0, v67
	v_rcp_f32_e32 v68, v67
	v_mul_f32_e32 v66, 0xc1000000, v66
	s_waitcnt vmcnt(0)
	v_mul_f32_e32 v66, v87, v66
	v_mul_f32_e32 v67, 0x3fb8aa3b, v66
	v_add_f32_e32 v66, v66, v66
	v_mul_f32_e32 v66, 0x3fb8aa3b, v66
	v_exp_f32_e32 v66, v66
	v_exp_f32_e32 v69, v67
	v_mfma_f32_16x16x32_bf16 v[44:47], v[24:27], v[56:59], v[44:47]
	v_sub_f32_e32 v66, 1.0, v66
	v_max_f32_e32 v66, 0, v66
	v_mfma_f32_16x16x32_bf16 v[28:31], v[20:23], v[28:31], 0
	v_sqrt_f32_e32 v67, v66
	v_mfma_f32_16x16x32_bf16 v[32:35], v[24:27], v[32:35], v[28:31]
	v_add_u32_e32 v70, -1, v67
	v_fma_f32 v74, -v70, v67, v66
	v_cmp_ge_f32_e64 s[4:5], 0, v74
	v_add_u32_e32 v74, 1, v67
	v_mfma_f32_16x16x32_bf16 v[28:31], v[20:23], v[36:39], 0
	v_cndmask_b32_e64 v70, v67, v70, s[4:5]
	v_fma_f32 v67, -v74, v67, v66
	v_cmp_lt_f32_e64 s[4:5], 0, v67
	v_mfma_f32_16x16x32_bf16 v[28:31], v[24:27], v[40:43], v[28:31]
	s_nop 0
	v_cndmask_b32_e64 v67, v70, v74, s[4:5]
	v_cmp_class_f32_e32 vcc, v66, v205
	s_movk_i32 s4, 0x108
	v_mfma_f32_16x16x32_bf16 v[4:7], v[20:23], v[4:7], 0
	v_cndmask_b32_e32 v66, v67, v66, vcc
	v_or_b32_e32 v67, v76, v92
	v_cmp_eq_u32_e32 vcc, 0, v67
	v_mfma_f32_16x16x32_bf16 v[8:11], v[24:27], v[8:11], v[4:7]
	s_nop 0
	v_cndmask_b32_e64 v70, v66, 1.0, vcc
	v_mad_u32_u24 v66, v92, s4, v91
	v_lshl_add_u32 v74, v66, 2, v79
	v_add_u32_e32 v75, 0x800, v74
	ds_read2_b32 v[66:67], v75 offset0:64 offset1:80
	v_mul_f32_e32 v68, v68, v70
	ds_write_b32 v74, v69 offset:6528
	v_mfma_f32_16x16x32_bf16 v[4:7], v[20:23], v[12:15], 0
	s_waitcnt lgkmcnt(1)
	v_mul_f32_e32 v66, v66, v68
	ds_write_b32 v74, v66 offset:2304
	v_add_f32_e32 v66, v83, v81
	v_mul_f32_e32 v66, 0xbfb8aa3b, v66
	v_exp_f32_e32 v66, v66
	v_add_f32_e32 v68, v71, v86
	v_mul_f32_e32 v68, 0xbfb8aa3b, v68
	v_exp_f32_e32 v68, v68
	v_add_f32_e32 v66, 1.0, v66
	v_rcp_f32_e32 v66, v66
	v_mfma_f32_16x16x32_bf16 v[4:7], v[24:27], v[16:19], v[4:7]
	v_add_f32_e32 v68, 1.0, v68
	v_rcp_f32_e32 v70, v68
	v_mul_f32_e32 v66, 0xc1000000, v66
	v_mul_f32_e32 v66, v87, v66
	v_mul_f32_e32 v68, 0x3fb8aa3b, v66
	v_add_f32_e32 v66, v66, v66
	v_mul_f32_e32 v66, 0x3fb8aa3b, v66
	v_exp_f32_e32 v66, v66
	v_exp_f32_e32 v71, v68
	v_sub_f32_e32 v66, 1.0, v66
	v_max_f32_e32 v66, 0, v66
	s_nop 0
	v_sqrt_f32_e32 v68, v66
	s_nop 0
	v_add_u32_e32 v69, -1, v68
	v_fma_f32 v76, -v69, v68, v66
	v_cmp_ge_f32_e64 s[6:7], 0, v76
	v_add_u32_e32 v76, 1, v68
	s_nop 0
	v_cndmask_b32_e64 v69, v68, v69, s[6:7]
	v_fma_f32 v68, -v76, v68, v66
	v_cmp_lt_f32_e64 s[6:7], 0, v68
	s_nop 1
	v_cndmask_b32_e64 v68, v69, v76, s[6:7]
	v_cmp_class_f32_e64 s[4:5], v66, v205
	s_nop 1
	v_cndmask_b32_e64 v66, v68, v66, s[4:5]
	ds_read2_b32 v[68:69], v75 offset0:130 offset1:146
	v_mul_f32_e32 v66, v70, v66
	ds_write_b32 v74, v71 offset:6792
	s_waitcnt lgkmcnt(1)
; __device__ __forceinline__ float fexp(float x) { return __builtin_amdgcn_exp2f(x * LOG2E); }
; __device__ __forceinline__ float sigm(float x) { return frcp(1.f + fexp(-x)); }
; __device__ __forceinline__ void lru_item(const Params& p, int l, int item, LAS unsigned char* lds) {
;     ...
;           const int cj = l * 256 + h * 64 + jt * 16 + fr; const float bav = p.ba[cj], bxv = p.bx[cj], sp = p.spl[cj];
; #pragma unroll
;           for (int jj = 0; jj < 4; ++jj) { const int t = fq * 4 + jj; const float r = sigm(pa[jj] + bav), ig = sigm(px[jj] + bxv); const float la = -8.f * r * sp;
;               const float a = fexp(la); float mult = sqrtf(fmaxf(1.f - fexp(2.f * la), 0.f)); if (t0 + t == 0) mult = 1.f;
;               const int li = t * 66 + jt * 16 + fr; const float xcv = xf[li]; sa[li] = a; xf[li] = mult * ig * xcv; }
	v_mul_f32_e32 v66, v68, v66
	ds_write_b32 v74, v66 offset:2568
	v_add_f32_e32 v66, v84, v81
	v_mul_f32_e32 v66, 0xbfb8aa3b, v66
	v_exp_f32_e32 v66, v66
	v_add_f32_e32 v68, v72, v86
	v_mul_f32_e32 v68, 0xbfb8aa3b, v68
	v_exp_f32_e32 v68, v68
	v_add_f32_e32 v66, 1.0, v66
	v_rcp_f32_e32 v66, v66
	v_add_f32_e32 v68, 1.0, v68
	v_rcp_f32_e32 v68, v68
	v_mul_f32_e32 v66, 0xc1000000, v66
	v_mul_f32_e32 v66, v87, v66
	v_mul_f32_e32 v70, 0x3fb8aa3b, v66
	v_add_f32_e32 v66, v66, v66
	v_mul_f32_e32 v66, 0x3fb8aa3b, v66
	v_exp_f32_e32 v66, v66
	v_exp_f32_e32 v72, v70
	v_sub_f32_e32 v66, 1.0, v66
	v_max_f32_e32 v66, 0, v66
	s_nop 0
	v_sqrt_f32_e32 v70, v66
	s_nop 0
	v_add_u32_e32 v71, -1, v70
	v_fma_f32 v76, -v71, v70, v66
	v_cmp_ge_f32_e64 s[6:7], 0, v76
	v_add_u32_e32 v76, 1, v70
	s_nop 0
	v_cndmask_b32_e64 v71, v70, v71, s[6:7]
	v_fma_f32 v70, -v76, v70, v66
	v_cmp_lt_f32_e64 s[6:7], 0, v70
	s_nop 1
	v_cndmask_b32_e64 v70, v71, v76, s[6:7]
	v_cmp_class_f32_e64 s[4:5], v66, v205
	s_nop 1
	v_cndmask_b32_e64 v66, v70, v66, s[4:5]
	ds_read2_b32 v[70:71], v75 offset0:196 offset1:212
	v_mul_f32_e32 v66, v68, v66
	v_add_f32_e32 v68, v73, v86
	v_mul_f32_e32 v68, 0xbfb8aa3b, v68
	v_exp_f32_e32 v68, v68
	s_waitcnt lgkmcnt(0)
	v_mul_f32_e32 v66, v70, v66
	ds_write_b32 v74, v66 offset:2832
	v_add_f32_e32 v66, v85, v81
	v_mul_f32_e32 v66, 0xbfb8aa3b, v66
	v_exp_f32_e32 v66, v66
	v_add_f32_e32 v68, 1.0, v68
	v_rcp_f32_e32 v70, v68
	ds_write_b32 v74, v72 offset:7056
	v_add_f32_e32 v66, 1.0, v66
	v_rcp_f32_e32 v66, v66
	s_nop 0
	v_mul_f32_e32 v66, 0xc1000000, v66
	v_mul_f32_e32 v66, v87, v66
	v_mul_f32_e32 v68, 0x3fb8aa3b, v66
	v_add_f32_e32 v66, v66, v66
	v_mul_f32_e32 v66, 0x3fb8aa3b, v66
	v_exp_f32_e32 v66, v66
	v_exp_f32_e32 v68, v68
	v_sub_f32_e32 v66, 1.0, v66
	v_max_f32_e32 v66, 0, v66
	s_nop 0
	v_sqrt_f32_e32 v72, v66
	s_nop 0
	v_add_u32_e32 v73, -1, v72
	v_fma_f32 v76, -v73, v72, v66
	v_cmp_ge_f32_e64 s[6:7], 0, v76
	v_add_u32_e32 v76, 1, v72
	s_nop 0
	v_cndmask_b32_e64 v73, v72, v73, s[6:7]
	v_fma_f32 v72, -v76, v72, v66
	v_cmp_lt_f32_e64 s[6:7], 0, v72
	s_nop 1
	v_cndmask_b32_e64 v72, v73, v76, s[6:7]
	v_cmp_class_f32_e64 s[4:5], v66, v205
	s_nop 1
	v_cndmask_b32_e64 v76, v72, v66, s[4:5]
	v_add_u32_e32 v66, 0xc00, v74
	ds_read2_b32 v[72:73], v66 offset0:6 offset1:22
	v_mov_b32_e32 v52, v159
	v_mov_b32_e32 v53, v160
	v_mov_b32_e32 v54, v161
	v_mul_f32_e32 v70, v70, v76
	s_waitcnt lgkmcnt(0)
	v_mul_f32_e32 v70, v72, v70
	s_waitcnt vmcnt(2)
	v_add_f32_e32 v48, v48, v52
	v_mul_f32_e32 v48, 0xbfb8aa3b, v48
	v_exp_f32_e32 v48, v48
	s_waitcnt vmcnt(1)
	v_add_f32_e32 v44, v44, v53
	v_mul_f32_e32 v44, 0xbfb8aa3b, v44
	v_exp_f32_e32 v44, v44
	v_add_f32_e32 v48, 1.0, v48
	v_rcp_f32_e32 v48, v48
	v_add_f32_e32 v45, v45, v53
	v_add_f32_e32 v44, 1.0, v44
	v_rcp_f32_e32 v44, v44
	v_mul_f32_e32 v48, 0xc1000000, v48
	s_waitcnt vmcnt(0)
	v_mul_f32_e32 v48, v54, v48
	v_mul_f32_e32 v55, 0x3fb8aa3b, v48
	v_add_f32_e32 v48, v48, v48
	v_mul_f32_e32 v48, 0x3fb8aa3b, v48
	v_exp_f32_e32 v48, v48
	v_exp_f32_e32 v55, v55
	v_mul_f32_e32 v45, 0xbfb8aa3b, v45
	v_exp_f32_e32 v45, v45
	v_sub_f32_e32 v48, 1.0, v48
	v_max_f32_e32 v48, 0, v48
	ds_write_b32 v74, v55 offset:6592
	v_sqrt_f32_e32 v56, v48
	v_add_f32_e32 v45, 1.0, v45
	v_rcp_f32_e32 v45, v45
	v_add_u32_e32 v57, -1, v56
	v_fma_f32 v58, -v57, v56, v48
	v_cmp_ge_f32_e64 s[6:7], 0, v58
	v_add_u32_e32 v58, 1, v56
	s_nop 0
	v_cndmask_b32_e64 v57, v56, v57, s[6:7]
	v_fma_f32 v56, -v58, v56, v48
	v_cmp_lt_f32_e64 s[6:7], 0, v56
	s_nop 1
	v_cndmask_b32_e64 v56, v57, v58, s[6:7]
	v_cmp_class_f32_e64 s[4:5], v48, v205
	s_nop 1
	v_cndmask_b32_e64 v48, v56, v48, s[4:5]
	v_cndmask_b32_e64 v48, v48, 1.0, vcc
	v_mul_f32_e32 v44, v44, v48
	v_mul_f32_e32 v48, v67, v44
	v_add_f32_e32 v44, v49, v52
	v_mul_f32_e32 v44, 0xbfb8aa3b, v44
	v_exp_f32_e32 v44, v44
	s_nop 0
	v_add_f32_e32 v44, 1.0, v44
	v_rcp_f32_e32 v44, v44
	s_nop 0
	v_mul_f32_e32 v44, 0xc1000000, v44
	v_mul_f32_e32 v44, v54, v44
	v_mul_f32_e32 v49, 0x3fb8aa3b, v44
	v_add_f32_e32 v44, v44, v44
	v_mul_f32_e32 v44, 0x3fb8aa3b, v44
	v_exp_f32_e32 v44, v44
	v_exp_f32_e32 v49, v49
	v_sub_f32_e32 v44, 1.0, v44
	v_max_f32_e32 v44, 0, v44
	ds_write_b32 v74, v49 offset:6856
	v_sqrt_f32_e32 v55, v44
	s_nop 0
	v_add_u32_e32 v56, -1, v55
	v_fma_f32 v57, -v56, v55, v44
	v_cmp_ge_f32_e64 s[6:7], 0, v57
	v_add_u32_e32 v57, 1, v55
	s_nop 0
	v_cndmask_b32_e64 v56, v55, v56, s[6:7]
	v_fma_f32 v55, -v57, v55, v44
	v_cmp_lt_f32_e64 s[6:7], 0, v55
	s_nop 1
	v_cndmask_b32_e64 v55, v56, v57, s[6:7]
	v_cmp_class_f32_e64 s[4:5], v44, v205
	s_nop 1
	v_cndmask_b32_e64 v44, v55, v44, s[4:5]
	v_mul_f32_e32 v44, v45, v44
	v_mul_f32_e32 v44, v69, v44
	ds_write_b32 v74, v44 offset:2632
	v_add_f32_e32 v44, v50, v52
	v_mul_f32_e32 v44, 0xbfb8aa3b, v44
	v_exp_f32_e32 v44, v44
	v_add_f32_e32 v45, v46, v53
	v_mul_f32_e32 v45, 0xbfb8aa3b, v45
	v_exp_f32_e32 v45, v45
	v_add_f32_e32 v44, 1.0, v44
	v_rcp_f32_e32 v44, v44
	v_add_f32_e32 v45, 1.0, v45
	v_rcp_f32_e32 v45, v45
	v_mul_f32_e32 v44, 0xc1000000, v44
	v_mul_f32_e32 v44, v54, v44
	v_mul_f32_e32 v46, 0x3fb8aa3b, v44
	v_add_f32_e32 v44, v44, v44
	v_mul_f32_e32 v44, 0x3fb8aa3b, v44
	v_exp_f32_e32 v44, v44
	v_exp_f32_e32 v46, v46
	v_sub_f32_e32 v44, 1.0, v44
	v_max_f32_e32 v44, 0, v44
	ds_write_b32 v74, v46 offset:7120
	v_sqrt_f32_e32 v49, v44
	s_nop 0
	v_add_u32_e32 v50, -1, v49
	v_fma_f32 v55, -v50, v49, v44
	v_cmp_ge_f32_e64 s[6:7], 0, v55
	v_add_u32_e32 v55, 1, v49
	s_nop 0
	v_cndmask_b32_e64 v50, v49, v50, s[6:7]
	v_fma_f32 v49, -v55, v49, v44
	v_cmp_lt_f32_e64 s[6:7], 0, v49
	s_nop 1
	v_cndmask_b32_e64 v49, v50, v55, s[6:7]
	v_cmp_class_f32_e64 s[4:5], v44, v205
	s_nop 1
	v_cndmask_b32_e64 v44, v49, v44, s[4:5]
	v_mul_f32_e32 v44, v45, v44
	v_mul_f32_e32 v44, v71, v44
	ds_write_b32 v74, v44 offset:2896
	v_add_f32_e32 v44, v51, v52
	v_mul_f32_e32 v44, 0xbfb8aa3b, v44
	v_exp_f32_e32 v44, v44
	v_add_f32_e32 v45, v47, v53
	v_mul_f32_e32 v45, 0xbfb8aa3b, v45
	v_exp_f32_e32 v45, v45
	v_add_f32_e32 v44, 1.0, v44
	v_rcp_f32_e32 v44, v44
	v_add_f32_e32 v45, 1.0, v45
	v_rcp_f32_e32 v45, v45
	v_mul_f32_e32 v44, 0xc1000000, v44
	v_mul_f32_e32 v44, v54, v44
	v_mul_f32_e32 v46, 0x3fb8aa3b, v44
	v_add_f32_e32 v44, v44, v44
	v_mul_f32_e32 v44, 0x3fb8aa3b, v44
	v_exp_f32_e32 v44, v44
	v_exp_f32_e32 v46, v46
	v_sub_f32_e32 v44, 1.0, v44
	v_max_f32_e32 v44, 0, v44
	s_nop 0
	v_sqrt_f32_e32 v47, v44
	s_nop 0
	v_add_u32_e32 v49, -1, v47
	v_fma_f32 v50, -v49, v47, v44
	v_cmp_ge_f32_e64 s[6:7], 0, v50
	v_add_u32_e32 v50, 1, v47
	s_nop 0
	v_cndmask_b32_e64 v49, v47, v49, s[6:7]
	v_fma_f32 v47, -v50, v47, v44
	v_cmp_lt_f32_e64 s[6:7], 0, v47
	s_nop 1
	v_cndmask_b32_e64 v47, v49, v50, s[6:7]
	v_cmp_class_f32_e64 s[4:5], v44, v205
	s_nop 1
	v_cndmask_b32_e64 v47, v47, v44, s[4:5]
	v_mul_f32_e32 v45, v45, v47
	v_add_u32_e32 v44, 0x1c00, v74
	v_mul_f32_e32 v45, v73, v45
	ds_write2_b32 v44, v68, v46 offset0:38 offset1:54
	ds_write2_b32 v66, v70, v45 offset0:6 offset1:22
	v_mov_b32_e32 v40, v162
	v_mov_b32_e32 v41, v163
	v_mov_b32_e32 v42, v164
	s_waitcnt vmcnt(2)
; __device__ __forceinline__ float fexp(float x) { return __builtin_amdgcn_exp2f(x * LOG2E); }
; __device__ __forceinline__ float sigm(float x) { return frcp(1.f + fexp(-x)); }
; __device__ __forceinline__ void lru_item(const Params& p, int l, int item, LAS unsigned char* lds) {
;     ...
;           const int cj = l * 256 + h * 64 + jt * 16 + fr; const float bav = p.ba[cj], bxv = p.bx[cj], sp = p.spl[cj];
; #pragma unroll
;           for (int jj = 0; jj < 4; ++jj) { const int t = fq * 4 + jj; const float r = sigm(pa[jj] + bav), ig = sigm(px[jj] + bxv); const float la = -8.f * r * sp;
;               const float a = fexp(la); float mult = sqrtf(fmaxf(1.f - fexp(2.f * la), 0.f)); if (t0 + t == 0) mult = 1.f;
;               const int li = t * 66 + jt * 16 + fr; const float xcv = xf[li]; sa[li] = a; xf[li] = mult * ig * xcv; }
	v_add_f32_e32 v32, v32, v40
	v_mul_f32_e32 v32, 0xbfb8aa3b, v32
	v_exp_f32_e32 v32, v32
	s_waitcnt vmcnt(1)
	v_add_f32_e32 v28, v28, v41
	v_mul_f32_e32 v28, 0xbfb8aa3b, v28
	v_exp_f32_e32 v28, v28
	v_add_f32_e32 v32, 1.0, v32
	v_rcp_f32_e32 v32, v32
	v_add_f32_e32 v29, v29, v41
	v_add_f32_e32 v28, 1.0, v28
	v_rcp_f32_e32 v28, v28
	v_mul_f32_e32 v32, 0xc1000000, v32
	s_waitcnt vmcnt(0)
	v_mul_f32_e32 v32, v42, v32
	v_mul_f32_e32 v36, 0x3fb8aa3b, v32
	v_add_f32_e32 v32, v32, v32
	v_mul_f32_e32 v32, 0x3fb8aa3b, v32
	v_exp_f32_e32 v32, v32
	v_exp_f32_e32 v36, v36
	v_mul_f32_e32 v29, 0xbfb8aa3b, v29
	v_exp_f32_e32 v29, v29
	v_sub_f32_e32 v32, 1.0, v32
	v_max_f32_e32 v32, 0, v32
	ds_write_b32 v74, v36 offset:6656
	v_sqrt_f32_e32 v37, v32
	v_add_f32_e32 v29, 1.0, v29
	v_rcp_f32_e32 v29, v29
	v_add_u32_e32 v38, -1, v37
	v_fma_f32 v39, -v38, v37, v32
	v_cmp_ge_f32_e64 s[6:7], 0, v39
	v_add_u32_e32 v39, 1, v37
	s_nop 0
	v_cndmask_b32_e64 v38, v37, v38, s[6:7]
	v_fma_f32 v37, -v39, v37, v32
	v_cmp_lt_f32_e64 s[6:7], 0, v37
	s_nop 1
	v_cndmask_b32_e64 v37, v38, v39, s[6:7]
	ds_read2_b32 v[38:39], v75 offset0:96 offset1:112
	v_cmp_class_f32_e64 s[4:5], v32, v205
	s_nop 1
	v_cndmask_b32_e64 v32, v37, v32, s[4:5]
	v_cndmask_b32_e64 v32, v32, 1.0, vcc
	v_mul_f32_e32 v28, v28, v32
	s_waitcnt lgkmcnt(0)
	v_mul_f32_e32 v28, v38, v28
	ds_write2_b32 v75, v48, v28 offset0:80 offset1:96
	v_add_f32_e32 v28, v33, v40
	v_mul_f32_e32 v28, 0xbfb8aa3b, v28
	v_exp_f32_e32 v28, v28
	s_nop 0
	v_add_f32_e32 v28, 1.0, v28
	v_rcp_f32_e32 v28, v28
	s_nop 0
	v_mul_f32_e32 v28, 0xc1000000, v28
	v_mul_f32_e32 v28, v42, v28
	v_mul_f32_e32 v32, 0x3fb8aa3b, v28
	v_add_f32_e32 v28, v28, v28
	v_mul_f32_e32 v28, 0x3fb8aa3b, v28
	v_exp_f32_e32 v28, v28
	v_exp_f32_e32 v32, v32
	v_sub_f32_e32 v28, 1.0, v28
	v_max_f32_e32 v28, 0, v28
	s_nop 0
	v_sqrt_f32_e32 v33, v28
	s_nop 0
	v_add_u32_e32 v36, -1, v33
	v_fma_f32 v37, -v36, v33, v28
	v_cmp_ge_f32_e64 s[6:7], 0, v37
	v_add_u32_e32 v37, 1, v33
	s_nop 0
	v_cndmask_b32_e64 v36, v33, v36, s[6:7]
	v_fma_f32 v33, -v37, v33, v28
	v_cmp_lt_f32_e64 s[6:7], 0, v33
	s_nop 1
	v_cndmask_b32_e64 v33, v36, v37, s[6:7]
	ds_read2_b32 v[36:37], v75 offset0:162 offset1:178
	v_cmp_class_f32_e64 s[4:5], v28, v205
	ds_write_b32 v74, v32 offset:6920
	s_nop 0
	v_cndmask_b32_e64 v28, v33, v28, s[4:5]
	v_mul_f32_e32 v28, v29, v28
	s_waitcnt lgkmcnt(1)
	v_mul_f32_e32 v28, v36, v28
	ds_write_b32 v74, v28 offset:2696
	v_add_f32_e32 v28, v34, v40
	v_mul_f32_e32 v28, 0xbfb8aa3b, v28
	v_exp_f32_e32 v28, v28
	v_add_f32_e32 v29, v30, v41
	v_mul_f32_e32 v29, 0xbfb8aa3b, v29
	v_exp_f32_e32 v29, v29
	v_add_f32_e32 v28, 1.0, v28
	v_rcp_f32_e32 v28, v28
	v_add_f32_e32 v29, 1.0, v29
	v_rcp_f32_e32 v29, v29
	v_mul_f32_e32 v28, 0xc1000000, v28
	v_mul_f32_e32 v28, v42, v28
	v_mul_f32_e32 v30, 0x3fb8aa3b, v28
	v_add_f32_e32 v28, v28, v28
	v_mul_f32_e32 v28, 0x3fb8aa3b, v28
	v_exp_f32_e32 v28, v28
	v_exp_f32_e32 v30, v30
	v_sub_f32_e32 v28, 1.0, v28
	v_max_f32_e32 v28, 0, v28
	s_nop 0
	v_sqrt_f32_e32 v32, v28
	s_nop 0
	v_add_u32_e32 v33, -1, v32
	v_fma_f32 v34, -v33, v32, v28
	v_cmp_ge_f32_e64 s[6:7], 0, v34
	v_add_u32_e32 v34, 1, v32
	s_nop 0
	v_cndmask_b32_e64 v33, v32, v33, s[6:7]
	v_fma_f32 v32, -v34, v32, v28
	v_cmp_lt_f32_e64 s[6:7], 0, v32
	s_nop 1
	v_cndmask_b32_e64 v32, v33, v34, s[6:7]
	v_cmp_class_f32_e64 s[4:5], v28, v205
	s_nop 1
	v_cndmask_b32_e64 v28, v32, v28, s[4:5]
	ds_read2_b32 v[32:33], v75 offset0:228 offset1:244
	v_mul_f32_e32 v28, v29, v28
	v_add_f32_e32 v29, v31, v41
	v_mul_f32_e32 v29, 0xbfb8aa3b, v29
	v_exp_f32_e32 v29, v29
	s_waitcnt lgkmcnt(0)
	v_mul_f32_e32 v28, v32, v28
	ds_write_b32 v74, v28 offset:2960
	v_add_f32_e32 v28, v35, v40
	v_mul_f32_e32 v28, 0xbfb8aa3b, v28
	v_exp_f32_e32 v28, v28
	v_add_f32_e32 v29, 1.0, v29
	v_rcp_f32_e32 v31, v29
	ds_write_b32 v74, v30 offset:7184
	v_add_f32_e32 v28, 1.0, v28
	v_rcp_f32_e32 v28, v28
	s_nop 0
	v_mul_f32_e32 v28, 0xc1000000, v28
	v_mul_f32_e32 v28, v42, v28
	v_mul_f32_e32 v29, 0x3fb8aa3b, v28
	v_add_f32_e32 v28, v28, v28
	v_mul_f32_e32 v28, 0x3fb8aa3b, v28
	v_exp_f32_e32 v28, v28
	v_exp_f32_e32 v30, v29
	v_sub_f32_e32 v28, 1.0, v28
	v_max_f32_e32 v28, 0, v28
	s_nop 0
	v_sqrt_f32_e32 v29, v28
	s_nop 0
	v_add_u32_e32 v32, -1, v29
	v_fma_f32 v34, -v32, v29, v28
	v_cmp_ge_f32_e64 s[6:7], 0, v34
	v_add_u32_e32 v34, 1, v29
	s_nop 0
	v_cndmask_b32_e64 v32, v29, v32, s[6:7]
	v_fma_f32 v29, -v34, v29, v28
	v_cmp_lt_f32_e64 s[6:7], 0, v29
	s_nop 1
	v_cndmask_b32_e64 v29, v32, v34, s[6:7]
	v_cmp_class_f32_e64 s[4:5], v28, v205
	s_nop 1
	v_cndmask_b32_e64 v32, v29, v28, s[4:5]
	ds_read2_b32 v[28:29], v66 offset0:38 offset1:54
	v_mov_b32_e32 v12, v165
	v_mov_b32_e32 v13, v166
	v_mov_b32_e32 v14, v167
	v_mul_f32_e32 v31, v31, v32
	s_waitcnt lgkmcnt(0)
	v_mul_f32_e32 v28, v28, v31
	s_waitcnt vmcnt(2)
	v_add_f32_e32 v8, v8, v12
	v_mul_f32_e32 v8, 0xbfb8aa3b, v8
	v_exp_f32_e32 v8, v8
	s_waitcnt vmcnt(1)
	v_add_f32_e32 v4, v4, v13
	v_mul_f32_e32 v4, 0xbfb8aa3b, v4
	v_exp_f32_e32 v4, v4
	v_add_f32_e32 v8, 1.0, v8
	v_rcp_f32_e32 v8, v8
	v_add_f32_e32 v5, v5, v13
	v_add_f32_e32 v4, 1.0, v4
	v_rcp_f32_e32 v4, v4
	v_mul_f32_e32 v8, 0xc1000000, v8
	s_waitcnt vmcnt(0)
; __device__ __forceinline__ float fexp(float x) { return __builtin_amdgcn_exp2f(x * LOG2E); }
; __device__ __forceinline__ float sigm(float x) { return frcp(1.f + fexp(-x)); }
; __device__ __forceinline__ void lds_barrier() { asm volatile("s_waitcnt lgkmcnt(0)" ::: "memory"); __builtin_amdgcn_s_barrier(); asm volatile("" ::: "memory"); }
; __device__ __forceinline__ void lru_item(const Params& p, int l, int item, LAS unsigned char* lds) {
;     ...
;           const int cj = l * 256 + h * 64 + jt * 16 + fr; const float bav = p.ba[cj], bxv = p.bx[cj], sp = p.spl[cj];
; #pragma unroll
;           for (int jj = 0; jj < 4; ++jj) { const int t = fq * 4 + jj; const float r = sigm(pa[jj] + bav), ig = sigm(px[jj] + bxv); const float la = -8.f * r * sp;
;               const float a = fexp(la); float mult = sqrtf(fmaxf(1.f - fexp(2.f * la), 0.f)); if (t0 + t == 0) mult = 1.f;
;               const int li = t * 66 + jt * 16 + fr; const float xcv = xf[li]; sa[li] = a; xf[li] = mult * ig * xcv; }
;       } }
;     lds_barrier();
	v_mul_f32_e32 v8, v14, v8
	v_mul_f32_e32 v15, 0x3fb8aa3b, v8
	v_add_f32_e32 v8, v8, v8
	v_mul_f32_e32 v8, 0x3fb8aa3b, v8
	v_exp_f32_e32 v8, v8
	v_exp_f32_e32 v15, v15
	v_mul_f32_e32 v5, 0xbfb8aa3b, v5
	v_exp_f32_e32 v5, v5
	v_sub_f32_e32 v8, 1.0, v8
	v_max_f32_e32 v8, 0, v8
	ds_write_b32 v74, v15 offset:6720
	v_sqrt_f32_e32 v16, v8
	v_add_f32_e32 v5, 1.0, v5
	v_rcp_f32_e32 v5, v5
	v_add_u32_e32 v17, -1, v16
	v_fma_f32 v18, -v17, v16, v8
	v_cmp_ge_f32_e64 s[6:7], 0, v18
	v_add_u32_e32 v18, 1, v16
	s_nop 0
	v_cndmask_b32_e64 v17, v16, v17, s[6:7]
	v_fma_f32 v16, -v18, v16, v8
	v_cmp_lt_f32_e64 s[6:7], 0, v16
	s_nop 1
	v_cndmask_b32_e64 v16, v17, v18, s[6:7]
	v_cmp_class_f32_e64 s[4:5], v8, v205
	s_nop 1
	v_cndmask_b32_e64 v8, v16, v8, s[4:5]
	v_cndmask_b32_e64 v8, v8, 1.0, vcc
	v_mul_f32_e32 v4, v4, v8
	v_mul_f32_e32 v4, v39, v4
	ds_write_b32 v74, v4 offset:2496
	v_add_f32_e32 v4, v9, v12
	v_mul_f32_e32 v4, 0xbfb8aa3b, v4
	v_exp_f32_e32 v4, v4
	s_nop 0
	v_add_f32_e32 v4, 1.0, v4
	v_rcp_f32_e32 v4, v4
	s_nop 0
	v_mul_f32_e32 v4, 0xc1000000, v4
	v_mul_f32_e32 v4, v14, v4
	v_mul_f32_e32 v8, 0x3fb8aa3b, v4
	v_add_f32_e32 v4, v4, v4
	v_mul_f32_e32 v4, 0x3fb8aa3b, v4
	v_exp_f32_e32 v4, v4
	v_exp_f32_e32 v8, v8
	v_sub_f32_e32 v4, 1.0, v4
	v_max_f32_e32 v4, 0, v4
	ds_write_b32 v74, v8 offset:6984
	v_sqrt_f32_e32 v9, v4
	s_nop 0
	v_add_u32_e32 v15, -1, v9
	v_fma_f32 v16, -v15, v9, v4
	v_cmp_ge_f32_e64 s[4:5], 0, v16
	v_add_u32_e32 v16, 1, v9
	s_nop 0
	v_cndmask_b32_e64 v15, v9, v15, s[4:5]
	v_fma_f32 v9, -v16, v9, v4
	v_cmp_lt_f32_e64 s[4:5], 0, v9
	s_nop 1
	v_cndmask_b32_e64 v9, v15, v16, s[4:5]
	v_cmp_class_f32_e32 vcc, v4, v205
	s_nop 1
	v_cndmask_b32_e32 v4, v9, v4, vcc
	v_mul_f32_e32 v4, v5, v4
	v_mul_f32_e32 v4, v37, v4
	ds_write_b32 v74, v4 offset:2760
	v_add_f32_e32 v4, v10, v12
	v_mul_f32_e32 v4, 0xbfb8aa3b, v4
	v_exp_f32_e32 v4, v4
	v_add_f32_e32 v5, v6, v13
	v_mul_f32_e32 v5, 0xbfb8aa3b, v5
	v_exp_f32_e32 v5, v5
	v_add_f32_e32 v4, 1.0, v4
	v_rcp_f32_e32 v4, v4
	v_add_f32_e32 v5, 1.0, v5
	v_rcp_f32_e32 v5, v5
	v_mul_f32_e32 v4, 0xc1000000, v4
	v_mul_f32_e32 v4, v14, v4
	v_mul_f32_e32 v6, 0x3fb8aa3b, v4
	v_add_f32_e32 v4, v4, v4
	v_mul_f32_e32 v4, 0x3fb8aa3b, v4
	v_exp_f32_e32 v4, v4
	v_exp_f32_e32 v6, v6
	v_sub_f32_e32 v4, 1.0, v4
	v_max_f32_e32 v4, 0, v4
	ds_write_b32 v74, v6 offset:7248
	v_sqrt_f32_e32 v8, v4
	s_nop 0
	v_add_u32_e32 v9, -1, v8
	v_fma_f32 v10, -v9, v8, v4
	v_cmp_ge_f32_e64 s[4:5], 0, v10
	v_add_u32_e32 v10, 1, v8
	s_nop 0
	v_cndmask_b32_e64 v9, v8, v9, s[4:5]
	v_fma_f32 v8, -v10, v8, v4
	v_cmp_lt_f32_e64 s[4:5], 0, v8
	s_nop 1
	v_cndmask_b32_e64 v8, v9, v10, s[4:5]
	v_cmp_class_f32_e32 vcc, v4, v205
	s_nop 1
	v_cndmask_b32_e32 v4, v8, v4, vcc
	v_mul_f32_e32 v4, v5, v4
	v_mul_f32_e32 v4, v33, v4
	ds_write_b32 v74, v4 offset:3024
	v_add_f32_e32 v4, v11, v12
	v_mul_f32_e32 v4, 0xbfb8aa3b, v4
	v_exp_f32_e32 v4, v4
	v_add_f32_e32 v5, v7, v13
	v_mul_f32_e32 v5, 0xbfb8aa3b, v5
	v_exp_f32_e32 v5, v5
	v_add_f32_e32 v4, 1.0, v4
	v_rcp_f32_e32 v4, v4
	v_add_f32_e32 v5, 1.0, v5
	v_rcp_f32_e32 v5, v5
	v_mul_f32_e32 v4, 0xc1000000, v4
	v_mul_f32_e32 v4, v14, v4
	v_mul_f32_e32 v6, 0x3fb8aa3b, v4
	v_add_f32_e32 v4, v4, v4
	v_mul_f32_e32 v4, 0x3fb8aa3b, v4
	v_exp_f32_e32 v4, v4
	v_exp_f32_e32 v6, v6
	v_lshl_add_u32 v14, v3, 2, v79
	v_sub_f32_e32 v4, 1.0, v4
	v_max_f32_e32 v4, 0, v4
	ds_write2_b32 v44, v30, v6 offset0:70 offset1:86
	v_sqrt_f32_e32 v7, v4
	s_nop 0
	v_add_u32_e32 v8, -1, v7
	v_fma_f32 v9, -v8, v7, v4
	v_cmp_ge_f32_e64 s[4:5], 0, v9
	v_add_u32_e32 v9, 1, v7
	s_nop 0
	v_cndmask_b32_e64 v8, v7, v8, s[4:5]
	v_fma_f32 v7, -v9, v7, v4
	v_cmp_lt_f32_e64 s[4:5], 0, v7
	s_nop 1
	v_cndmask_b32_e64 v7, v8, v9, s[4:5]
	v_cmp_class_f32_e32 vcc, v4, v205
	s_nop 1
	v_cndmask_b32_e32 v4, v7, v4, vcc
	v_mul_f32_e32 v4, v5, v4
	v_mul_f32_e32 v4, v29, v4
	ds_write2_b32 v66, v28, v4 offset0:38 offset1:54
	s_waitcnt lgkmcnt(0)
	s_barrier
; __device__ __forceinline__ void lds_barrier() { asm volatile("s_waitcnt lgkmcnt(0)" ::: "memory"); __builtin_amdgcn_s_barrier(); asm volatile("" ::: "memory"); }
; __device__ __forceinline__ void lru_item(const Params& p, int l, int item, LAS unsigned char* lds) {
;     ...
;     lds_barrier();
;     float Ac[16], Hl[16];
;     { float A = 1.f, H = 0.f;
; #pragma unroll
;       for (int i = 0; i < 16; ++i) { const float a = sa[i * 66 + lane], bt = xf[i * 66 + lane]; H = a * H + bt; A *= a; Ac[i] = A; Hl[i] = H; }
;       ct[(wid * 64 + lane) * 2] = A; ct[(wid * 64 + lane) * 2 + 1] = H; }
;     lds_barrier();
;     { float Ain = 1.f, Hin = 0.f;
;       for (int w = 0; w < wid; ++w) { const float aw = ct[(w * 64 + lane) * 2], hw = ct[(w * 64 + lane) * 2 + 1]; Hin = aw * Hin + hw; Ain *= aw; }
	v_add_u32_e32 v4, 0x1800, v14
	ds_read2_b32 v[22:23], v4 offset0:30 offset1:96
	ds_read_b32 v18, v80 offset:2304
	ds_read2_b32 v[6:7], v4 offset0:162 offset1:228
	v_add_u32_e32 v4, 0x800, v14
	ds_read2_b32 v[20:21], v4 offset0:130 offset1:196
	v_add_u32_e32 v4, 0x1c00, v14
	v_add_u32_e32 v5, 0xc00, v14
	ds_read2_b32 v[8:9], v4 offset0:38 offset1:104
	ds_read2_b32 v[12:13], v5 offset0:6 offset1:72
	s_waitcnt lgkmcnt(4)
	v_fmac_f32_e32 v18, 0, v23
	ds_read2_b32 v[46:47], v4 offset0:170 offset1:236
	ds_read2_b32 v[10:11], v5 offset0:138 offset1:204
	s_waitcnt lgkmcnt(4)
	v_fma_f32 v19, v18, v6, v20
	v_fmac_f32_e32 v21, v19, v7
	s_waitcnt lgkmcnt(2)
	v_fma_f32 v25, v21, v8, v12
	v_fmac_f32_e32 v13, v25, v9
	v_mul_f32_e32 v28, v23, v6
	s_waitcnt lgkmcnt(0)
	v_fma_f32 v17, v13, v46, v10
	v_add_u32_e32 v6, 0x2000, v14
	v_add_u32_e32 v10, 0x1000, v14
	ds_read2_b32 v[40:41], v6 offset0:46 offset1:112
	ds_read2_b32 v[4:5], v10 offset0:14 offset1:80
	ds_read2_b32 v[38:39], v6 offset0:178 offset1:244
	ds_read2_b32 v[42:43], v10 offset0:146 offset1:212
	v_fmac_f32_e32 v11, v17, v47
	v_mov_b32_e32 v6, v7
	v_mov_b32_e32 v26, v8
	s_waitcnt lgkmcnt(2)
	v_fma_f32 v15, v11, v40, v4
	v_fmac_f32_e32 v5, v15, v41
	v_mov_b32_e32 v29, v5
	s_waitcnt lgkmcnt(1)
	v_mov_b32_e32 v7, v38
	v_add_u32_e32 v4, 0x2400, v14
	v_pk_mul_f32 v[32:33], v[28:29], v[6:7]
	s_waitcnt lgkmcnt(0)
	v_mov_b32_e32 v27, v42
	ds_read2_b32 v[48:49], v4 offset0:54 offset1:120
	v_pk_mul_f32 v[36:37], v[32:33], v[26:27]
	v_pk_fma_f32 v[6:7], v[28:29], v[6:7], v[26:27]
	v_mov_b32_e32 v8, v9
	v_mov_b32_e32 v37, v7
	v_mov_b32_e32 v9, v39
	v_pk_mul_f32 v[26:27], v[36:37], v[8:9]
	v_mov_b32_e32 v42, v46
	v_add_u32_e32 v6, 0x1400, v14
	v_pk_mul_f32 v[30:31], v[26:27], v[42:43]
	v_pk_fma_f32 v[8:9], v[36:37], v[8:9], v[42:43]
	ds_read2_b32 v[50:51], v6 offset0:22 offset1:88
	ds_read2_b32 v[42:43], v4 offset0:186 offset1:252
	ds_read2_b32 v[44:45], v6 offset0:154 offset1:220
	ds_read_b32 v67, v14 offset:10488
	v_mov_b32_e32 v31, v9
	v_mov_b32_e32 v46, v47
	s_waitcnt lgkmcnt(4)
	v_mov_b32_e32 v47, v48
	v_pk_mul_f32 v[60:61], v[30:31], v[46:47]
	v_mov_b32_e32 v52, v40
	s_waitcnt lgkmcnt(3)
	v_mov_b32_e32 v53, v50
	v_pk_mul_f32 v[64:65], v[60:61], v[52:53]
	v_pk_fma_f32 v[52:53], v[30:31], v[46:47], v[52:53]
	v_mov_b32_e32 v40, v41
	v_mov_b32_e32 v65, v53
	v_mov_b32_e32 v41, v49
	v_pk_mul_f32 v[54:55], v[64:65], v[40:41]
	v_mov_b32_e32 v50, v38
	v_pk_mul_f32 v[58:59], v[54:55], v[50:51]
	v_pk_fma_f32 v[40:41], v[64:65], v[40:41], v[50:51]
	v_mov_b32_e32 v38, v39
	v_mov_b32_e32 v59, v41
	s_waitcnt lgkmcnt(2)
	v_mov_b32_e32 v39, v42
	v_pk_mul_f32 v[56:57], v[58:59], v[38:39]
	v_mov_b32_e32 v46, v48
	s_waitcnt lgkmcnt(1)
	v_mov_b32_e32 v47, v44
	v_pk_mul_f32 v[62:63], v[56:57], v[46:47]
	v_pk_fma_f32 v[46:47], v[58:59], v[38:39], v[46:47]
	v_mov_b32_e32 v38, v49
	v_mov_b32_e32 v63, v47
	v_mov_b32_e32 v39, v43
	v_pk_mul_f32 v[48:49], v[62:63], v[38:39]
	v_mov_b32_e32 v44, v42
	v_pk_mul_f32 v[50:51], v[48:49], v[44:45]
	v_pk_fma_f32 v[38:39], v[62:63], v[38:39], v[44:45]
	v_mov_b32_e32 v66, v43
	v_mov_b32_e32 v51, v39
	s_waitcnt lgkmcnt(0)
	v_pk_mul_f32 v[44:45], v[50:51], v[66:67]
	v_mov_b32_e32 v68, v67
	v_mov_b32_e32 v69, v22
	v_pk_mul_f32 v[42:43], v[44:45], v[68:69]
	v_pk_fma_f32 v[66:67], v[50:51], v[66:67], v[68:69]
	v_mul_f32_e32 v34, 0, v23
	v_mov_b32_e32 v43, v67
	ds_write_b64 v1, v[42:43]
	s_waitcnt lgkmcnt(0)
	s_barrier
	v_cmp_lt_i32_e32 vcc, 0, v0
	v_mov_b32_e32 v8, 1.0
	s_and_saveexec_b64 s[4:5], vcc
	s_cbranch_execz .LBB0_397
	v_readlane_b32 s6, v255, 9
	v_mov_b32_e32 v8, 1.0
	v_mov_b32_e32 v77, 0
	v_lshl_add_u32 v1, v3, 3, s6
	s_mov_b64 s[6:7], 0
	v_mov_b32_e32 v4, v0
